# sel: during the radix stage wave 0 touches the next unit's indexer-q rows and head-weight rows (one dword per 128-byte line) so the next unit's fragment loads hit L2
# speedup vs baseline: 1.0025x; 1.0025x over previous
.LBB0_843:
	v_readfirstlane_b32 s100, v194
	s_cmp_lt_u32 s100, 64
	s_cbranch_scc0 .Lqt_skip
	s_waitcnt vmcnt(0)
	v_readfirstlane_b32 s98, v240
	s_sub_i32 s99, s98, 64
	s_xor_b32 s99, s99, 0x3ff
	s_add_i32 s99, s99, 64
	s_cmp_lt_i32 s98, 64
	s_cselect_b32 s98, s98, s99
	s_cmp_gt_i32 s98, 63
	s_cbranch_scc0 .Lqt_samp
	s_sub_i32 s99, s98, 64
	s_lshr_b32 s100, s99, 10
	s_lshl_b32 s99, s99, 3
	s_and_b32 s99, s99, 0x1ff8
	s_lshl_b32 s100, s100, 13
	s_or_b32 s99, s100, s99
	s_branch .Lqt_go
.Lqt_samp:
	s_ashr_i32 s99, s98, 1
	s_lshl_b32 s100, s98, 3
	s_and_b32 s100, s100, 8
	s_lshl_b32 s99, s99, 4
	s_or_b32 s99, s99, s100
	s_add_i32 s99, s99, 0x10000
.Lqt_go:
	s_min_u32 s99, s99, 0x101f8
	s_lshl_b32 s100, s99, 10
	s_add_u32 s100, s14, s100
	s_addc_u32 s101, s15, 0
	v_lshlrev_b32_e32 v248, 7, v194
	global_load_dword v249, v248, s[100:101]
	s_lshl_b32 s100, s99, 5
	s_add_u32 s100, s16, s100
	s_addc_u32 s101, s17, 0
	v_and_b32_e32 v250, 3, v194
	v_lshlrev_b32_e32 v250, 6, v250
	global_load_dword v251, v250, s[100:101]
